# retention: next step's K/V prefetch loads issued before the staging barrier (right after the last LDS staging write) instead of after it
# baseline (speedup 1.0000x reference)
.LBB0_117:
	s_waitcnt vmcnt(12)
	v_cvt_pk_bf16_f32 v104, v100, v101
	v_cvt_pk_bf16_f32 v105, v102, v103
	v_cvt_pk_bf16_f32 v106, v96, v97
	v_cvt_pk_bf16_f32 v107, v98, v99
	ds_write2_b64 v215, v[104:105], v[106:107] offset1:4
	v_cvt_pk_bf16_f32 v104, v92, v93
	v_cvt_pk_bf16_f32 v105, v94, v95
	v_cvt_pk_bf16_f32 v106, v88, v89
	v_cvt_pk_bf16_f32 v107, v90, v91
	ds_write2_b64 v215, v[104:105], v[106:107] offset0:8 offset1:12
	v_cvt_pk_bf16_f32 v104, v84, v85
	v_cvt_pk_bf16_f32 v105, v86, v87
	v_cvt_pk_bf16_f32 v106, v80, v81
	v_cvt_pk_bf16_f32 v107, v82, v83
	ds_write2_b64 v216, v[104:105], v[106:107] offset0:160 offset1:164
	v_cvt_pk_bf16_f32 v104, v76, v77
	v_cvt_pk_bf16_f32 v105, v78, v79
	v_cvt_pk_bf16_f32 v106, v72, v73
	v_cvt_pk_bf16_f32 v107, v74, v75
	ds_write2_b64 v216, v[104:105], v[106:107] offset0:168 offset1:172
	ds_write_b128 v217, v[0:3]
	ds_write_b128 v218, v[4:7]
	ds_write_b128 v219, v[8:11]
	ds_write_b128 v220, v[12:15]
	ds_write_b128 v221, v[28:31]
	ds_write_b128 v222, v[44:47]
	ds_write_b128 v223, v[56:59]
	ds_write_b128 v224, v[60:63]
	ds_write_b128 v225, v[64:67]
	v_lshlrev_b32_e32 v104, 16, v64
	v_and_b32_e32 v105, 0xffff0000, v64
	v_mul_f32_e32 v104, v246, v104
	v_mul_f32_e32 v105, v246, v105
	v_cvt_pk_bf16_f32 v104, v104, v105
	v_lshlrev_b32_e32 v105, 16, v65
	v_and_b32_e32 v106, 0xffff0000, v65
	v_mul_f32_e32 v105, v246, v105
	v_mul_f32_e32 v106, v246, v106
	v_cvt_pk_bf16_f32 v105, v105, v106
	v_lshlrev_b32_e32 v106, 16, v66
	v_and_b32_e32 v107, 0xffff0000, v66
	v_mul_f32_e32 v106, v246, v106
	v_mul_f32_e32 v107, v246, v107
	v_cvt_pk_bf16_f32 v106, v106, v107
	v_lshlrev_b32_e32 v107, 16, v67
	v_mul_f32_e32 v107, v246, v107
	v_and_b32_e32 v108, 0xffff0000, v67
	v_mul_f32_e32 v108, v246, v108
	v_cvt_pk_bf16_f32 v107, v107, v108
	ds_write_b128 v226, v[104:107]
	ds_write_b128 v227, v[68:71]
	v_lshlrev_b32_e32 v104, 16, v68
	v_and_b32_e32 v105, 0xffff0000, v68
	v_mul_f32_e32 v104, v247, v104
	v_mul_f32_e32 v105, v247, v105
	v_cvt_pk_bf16_f32 v104, v104, v105
	v_lshlrev_b32_e32 v105, 16, v69
	v_and_b32_e32 v106, 0xffff0000, v69
	v_mul_f32_e32 v105, v247, v105
	v_mul_f32_e32 v106, v247, v106
	v_cvt_pk_bf16_f32 v105, v105, v106
	v_lshlrev_b32_e32 v106, 16, v70
	v_and_b32_e32 v107, 0xffff0000, v70
	s_add_i32 s51, s52, 1
	v_mul_f32_e32 v106, v247, v106
	v_mul_f32_e32 v107, v247, v107
	s_cmp_ge_u32 s51, s45
	v_cvt_pk_bf16_f32 v106, v106, v107
	v_lshlrev_b32_e32 v107, 16, v71
	s_cselect_b64 s[12:13], -1, 0
	s_cmp_lt_u32 s51, s45
	v_mul_f32_e32 v107, v247, v107
	v_and_b32_e32 v108, 0xffff0000, v71
	s_cselect_b64 s[14:15], -1, 0
	s_and_b64 vcc, exec, s[12:13]
	v_mul_f32_e32 v108, v247, v108
	v_cvt_pk_bf16_f32 v107, v107, v108
	ds_write_b128 v228, v[104:107]
	s_cbranch_vccnz .Lret_nopref
	s_sub_i32 s11, s49, s51
	s_and_b64 s[34:35], s[0:1], exec
	s_cselect_b32 s11, s51, s11
	s_lshl_b32 s11, s11, 7
	s_add_i32 s53, s11, s48
	s_mul_hi_i32 s55, s53, s69
	s_mul_i32 s54, s53, s69
	v_mad_u32_u24 v120, v236, s69, v144
	v_mad_u32_u24 v121, v237, s69, v144
	s_add_u32 s54, s54, s42
	s_addc_u32 s55, s55, s43
	v_mad_u32_u24 v122, v238, s69, v144
	v_mad_u32_u24 v123, v239, s69, v144
	s_add_u32 s34, s46, s68
	s_addc_u32 s35, 0, 0
	v_mad_u32_u24 v124, v240, s69, v144
	v_mad_u32_u24 v125, v241, s69, v144
	s_add_u32 s34, s34, s54
	s_addc_u32 s35, s35, s55
	v_mad_u32_u24 v126, v242, s69, v144
	v_mad_u32_u24 v127, v243, s69, v144
	s_add_u32 s100, s46, s10
	s_addc_u32 s101, 0, 0
	v_mad_u32_u24 v128, v244, s69, v156
	v_mad_u32_u24 v129, v245, s69, v156
	s_add_u32 s100, s100, 0x2000
	s_addc_u32 s101, s101, 0
	v_mov_b32_e32 v157, v145
	s_add_u32 s100, s100, s54
	s_addc_u32 s101, s101, s55
	global_load_dwordx4 v[0:3], v120, s[34:35]
	global_load_dwordx4 v[4:7], v121, s[34:35]
	global_load_dwordx4 v[8:11], v122, s[34:35]
	global_load_dwordx4 v[12:15], v123, s[34:35]
	global_load_dwordx4 v[28:31], v124, s[34:35]
	global_load_dwordx4 v[44:47], v125, s[34:35]
	global_load_dwordx4 v[56:59], v126, s[34:35]
	global_load_dwordx4 v[60:63], v127, s[34:35]
	global_load_dwordx4 v[64:67], v128, s[100:101] nt
	global_load_dwordx4 v[68:71], v129, s[100:101] nt
.Lret_nopref:
	s_waitcnt lgkmcnt(0)
	s_barrier
	s_cbranch_vccnz .Lret_last
	s_waitcnt vmcnt(10)
	s_branch .LBB0_119
